# v106 = v102 with P1 K-loop per-segment setprio toggles replaced by one static s_setprio 1 for the trailing wave half (waves 4-7)
# speedup vs baseline: 1.0002x; 1.0002x over previous
; #define PG8_STAGE(bufoff, gbase, voff) do { _Pragma("unroll") for (int _i = 0; _i < 2; ++_i) \
;         __builtin_amdgcn_global_load_lds((const unsigned*)((const char*)(gbase) + (voff)[_i]), (PG8_LAS unsigned*)(lds + (bufoff) + ldsw + _i * 8192), 16, 0, 0); } while (0)
; #define PG8_BAR __builtin_amdgcn_s_barrier()
; template <class Epi, class Sched, bool ALIGN_EPI = false, bool SP2 = false>
; __device__ __forceinline__ void gemm_phase(PG8_LAS unsigned char* lds, const Gemm g, const Sched& S, const Epi& E) {
;     ...
;     for (int i = 0; i < 2; ++i) { int R, C; stage_rc(tid * 16 + i * 8192, R, C); const int Rb = Epi::PERM ? ((R & ~31) + perm32(R & 31)) : R;
;         voffA[i] = (unsigned)(R * K + C) * 2u; voffB[i] = (unsigned)(Rb * K + C) * 2u; }
;     const size_t kstep = (size_t)(BK * 2);
;     const size_t hstep = (size_t)HALF * K * 2;
;     const size_t tstep = 2 * hstep;
;     const unsigned ldsw = (unsigned)wid * 1024u;
;     const int aoff = lds_byte(wr * 64 + fr, fq * 8), boff = lds_byte(wc * 32 + fr, fq * 8);
;     ...
;     const char* cA = (const char*)g.A + (size_t)cur.pm * tstep; const char* cB = (const char*)g.Bt + (size_t)cur.pn * tstep;
;     S.a_ready(cur);
;     if constexpr (SP2) {
;         PG8_STAGE(PG8_SB(0, 0), cB, voffB); PG8_STAGE(PG8_SB(0, 1), cB + hstep, voffB); PG8_STAGE(PG8_SA(0, 0), cA, voffA); PG8_STAGE(PG8_SA(0, 1), cA + hstep, voffA);
;         if (wr == 1) PG8_BAR;
.LBB0_135:
	v_lshrrev_b32_e32 v3, 1, v0
	v_lshrrev_b32_e32 v4, 5, v0
	v_writelane_b32 v236, s18, 4
	v_lshlrev_b32_e32 v1, 4, v0
	v_and_b32_e32 v2, 32, v0
	v_and_b32_e32 v3, 24, v3
	v_and_b32_e32 v4, 4, v4
	v_bfe_u32 v5, v0, 2, 2
	v_writelane_b32 v236, s19, 5
	v_bfe_u32 v12, v0, 2, 4
	v_bitop3_b32 v10, v1, v2, 48 bitop3:0x6c
	v_and_b32_e32 v11, 64, v0
	v_or3_b32 v3, v4, v5, v3
	v_lshrrev_b32_e32 v4, 3, v0
	v_or_b32_e32 v13, 0x2000, v1
	v_writelane_b32 v236, s85, 6
	v_or_b32_e32 v2, v10, v11
	v_and_or_b32 v5, v4, 48, v12
	v_and_or_b32 v4, v4, 32, v3
	v_lshrrev_b32_e32 v1, 7, v13
	s_movk_i32 s0, 0x70
	v_writelane_b32 v236, s84, 7
	s_lshr_b32 s1, s6, 6
	v_lshl_or_b32 v148, v4, 11, v2
	v_and_or_b32 v4, v1, s0, v12
	s_movk_i32 s0, 0x60
	v_writelane_b32 v236, s72, 8
	v_and_or_b32 v1, v1, s0, v3
	s_lshr_b32 s0, s6, 8
	s_lshl_b32 s97, s1, 10
	v_writelane_b32 v236, s98, 9
	s_add_u32 s98, s14, 0x1200000
	s_addc_u32 s99, s15, 0
	s_add_u32 s4, s14, 0x200000
	s_addc_u32 s5, s15, 0
	s_ashr_i32 s23, s22, 31
	s_ashr_i32 s11, s10, 31
	s_lshl_b64 s[8:9], s[22:23], 19
	s_lshl_b64 s[18:19], s[10:11], 19
	s_add_u32 s90, s4, s18
	s_addc_u32 s91, s5, s19
	s_add_i32 s58, s97, 0
	s_add_i32 m0, s58, 0x10000
	v_lshl_or_b32 v152, v1, 11, v2
	global_load_lds_dwordx4 v148, s[90:91]
	s_add_i32 m0, s58, 0x12000
	s_add_u32 s18, s90, 0x40000
	global_load_lds_dwordx4 v152, s[90:91]
	s_addc_u32 s19, s91, 0
	s_add_i32 m0, s58, 0x14000
	v_lshl_or_b32 v146, v5, 11, v2
	global_load_lds_dwordx4 v148, s[18:19]
	s_add_i32 m0, s58, 0x16000
	s_add_u32 s88, s98, s8
	s_addc_u32 s89, s99, s9
	s_add_i32 s59, s58, 0x2000
	global_load_lds_dwordx4 v152, s[18:19]
	s_mov_b32 m0, s58
	s_add_u32 s8, s88, 0x40000
	v_lshl_or_b32 v150, v4, 11, v2
	global_load_lds_dwordx4 v146, s[88:89]
	s_mov_b32 m0, s59
	s_addc_u32 s9, s89, 0
	s_add_i32 s56, s58, 0x4000
	global_load_lds_dwordx4 v150, s[88:89]
	s_mov_b32 m0, s56
	s_add_i32 s57, s58, 0x6000
	global_load_lds_dwordx4 v146, s[8:9]
	s_mov_b32 m0, s57
	v_mov_b32_e32 v155, 0
	global_load_lds_dwordx4 v150, s[8:9]
	v_mov_b32_e32 v149, v155
	v_mov_b32_e32 v153, v155
	v_mov_b32_e32 v147, v155
	v_mov_b32_e32 v151, v155
	s_cmp_eq_u32 s0, 1
	s_mov_b32 s23, 0
	v_lshl_add_u64 v[8:9], s[90:91], 0, v[148:149]
	v_lshl_add_u64 v[6:7], s[90:91], 0, v[152:153]
	v_lshl_add_u64 v[2:3], s[88:89], 0, v[146:147]
	s_cselect_b64 s[24:25], -1, 0
	s_cmp_lg_u32 s0, 1
	v_lshl_add_u64 v[4:5], s[88:89], 0, v[150:151]
	s_cbranch_scc1 .LBB0_137
	s_setprio 1
	s_barrier

; #define PG8_STAGE(bufoff, gbase, voff) do { _Pragma("unroll") for (int _i = 0; _i < 2; ++_i) \
;         __builtin_amdgcn_global_load_lds((const unsigned*)((const char*)(gbase) + (voff)[_i]), (PG8_LAS unsigned*)(lds + (bufoff) + ldsw + _i * 8192), 16, 0, 0); } while (0)
; #define PG8_LDA(dst, b, h) do { _Pragma("unroll") for (int m = 0; m < 4; ++m) _Pragma("unroll") for (int k = 0; k < 2; ++k) dst[m][k] = *(const PG8_LAS bf16x8*)(lds + PG8_SA(b, h) + aoff + m * 2048 + k * 1024); } while (0)
; #define PG8_LDB(dst, b, h) do { _Pragma("unroll") for (int n = 0; n < 2; ++n) _Pragma("unroll") for (int k = 0; k < 2; ++k) dst[n][k] = *(const PG8_LAS bf16x8*)(lds + PG8_SB(b, h) + boff + n * 2048 + k * 1024); } while (0)
; #define PG8_MMA(ai, bj, At, Bt) do { __builtin_amdgcn_s_setprio(1); _Pragma("unroll") for (int m = 0; m < 4; ++m) _Pragma("unroll") for (int n = 0; n < 2; ++n) _Pragma("unroll") for (int k = 0; k < 2; ++k) \
;         acc[ai][bj][m][n] = __builtin_amdgcn_mfma_f32_16x16x32_bf16(Bt[n][k], At[m][k], acc[ai][bj][m][n], 0, 0, 0); __builtin_amdgcn_s_setprio(0); } while (0)
; #define PG8_WAIT_V(n) asm volatile("s_waitcnt vmcnt(" #n ")" ::: "memory")
; #define PG8_WAIT_L(n) asm volatile("s_waitcnt lgkmcnt(" #n ")" ::: "memory")
; #define PG8_BAR __builtin_amdgcn_s_barrier()
; template <class Epi, class Sched, bool ALIGN_EPI = false, bool SP2 = false>
; __device__ __forceinline__ void gemm_phase(PG8_LAS unsigned char* lds, const Gemm g, const Sched& S, const Epi& E) {
;     ...
;             const char* a1 = cA + (size_t)(t + 1) * kstep;
;             const char* a2 = last ? nA : cA + (size_t)(t + 2) * kstep; const char* b2 = last ? nB : cB + (size_t)(t + 2) * kstep;
;             const char* a3 = a2 + kstep; const char* b3 = b2 + kstep;
;             if (last && has_next) S.a_ready(nxt);
;             if constexpr (SP2) {
;             PG8_LDB(B0, 0, 0); PG8_LDB(B1, 0, 1); PG8_SCHED; PG8_LDA(At, 0, 0); PG8_STAGE(PG8_SA(1, 1), a1 + hstep, voffA);
;             PG8_WAIT_V(8); PG8_WAIT_L(0); PG8_BAR; PG8_MMA(0, 0, At, B0); PG8_MMA(0, 1, At, B1); PG8_BAR; PG8_SCHED;
;             PG8_LDA(At, 0, 1); PG8_STAGE(PG8_SB(0, 0), b2, voffB); PG8_STAGE(PG8_SB(0, 1), b2 + hstep, voffB); PG8_STAGE(PG8_SA(0, 0), a2, voffA);
;             PG8_WAIT_V(8); PG8_WAIT_L(0); PG8_BAR; PG8_MMA(1, 0, At, B0); PG8_MMA(1, 1, At, B1); PG8_BAR; PG8_SCHED;
.LBB0_142:
	s_ashr_i32 s81, s80, 31
	s_lshl_b64 s[84:85], s[80:81], 19
	s_add_u32 s84, s98, s84
	s_addc_u32 s85, s99, s85
	s_and_b64 s[86:87], s[8:9], exec
	s_cselect_b32 s1, s85, s89
	s_cselect_b32 s11, s84, s88
	s_ashr_i32 s83, s82, 31
	s_lshl_b64 s[86:87], s[82:83], 19
	s_add_u32 s86, s4, s86
	s_addc_u32 s87, s5, s87
	s_and_b64 s[92:93], s[8:9], exec
	s_cselect_b32 s79, s87, s91
	s_cselect_b32 s81, s86, s90
	s_add_u32 s88, s88, 0x40080
	s_addc_u32 s89, s89, 0
	s_add_u32 s83, s90, 0x100
	s_addc_u32 vcc_lo, s91, 0
	s_mov_b32 vcc_hi, -2
	s_add_u32 s90, s88, 0xfffc0080
	s_addc_u32 s91, s89, -1
	s_cmp_eq_u32 vcc_hi, 12
	s_cselect_b32 s93, s1, s91
	s_cselect_b32 s92, s11, s90
	s_cselect_b32 s91, s79, vcc_lo
	s_cselect_b32 s90, s81, s83
	v_lshl_add_u64 v[190:191], s[88:89], 0, v[156:157]
	s_add_i32 m0, s58, 0xc000
	global_load_lds_dwordx4 v[190:191], off
	v_lshl_add_u64 v[190:191], s[88:89], 0, v[158:159]
	s_add_i32 m0, s58, 0xe000
	s_nop 0
	global_load_lds_dwordx4 v[190:191], off
	s_waitcnt vmcnt(8)
	s_waitcnt lgkmcnt(0)
	s_barrier
	s_waitcnt lgkmcnt(0)
	v_mfma_f32_16x16x32_bf16 v[126:129], v[130:133], v[182:185], 0
	v_mfma_f32_16x16x32_bf16 v[122:125], v[138:141], v[182:185], 0
	v_mfma_f32_16x16x32_bf16 v[110:113], v[130:133], v[200:203], 0
	v_mfma_f32_16x16x32_bf16 v[106:109], v[138:141], v[200:203], 0
	v_mfma_f32_16x16x32_bf16 v[94:97], v[130:133], v[208:211], 0
	v_mfma_f32_16x16x32_bf16 v[90:93], v[138:141], v[208:211], 0
	v_mfma_f32_16x16x32_bf16 v[78:81], v[130:133], v[216:219], 0
	v_mfma_f32_16x16x32_bf16 v[74:77], v[138:141], v[216:219], 0
	v_mfma_f32_16x16x32_bf16 v[126:129], v[134:137], v[186:189], v[126:129]
	v_mfma_f32_16x16x32_bf16 v[122:125], v[142:145], v[186:189], v[122:125]
	v_mfma_f32_16x16x32_bf16 v[110:113], v[134:137], v[204:207], v[110:113]
	v_mfma_f32_16x16x32_bf16 v[106:109], v[142:145], v[204:207], v[106:109]
	v_mfma_f32_16x16x32_bf16 v[94:97], v[134:137], v[212:215], v[94:97]
	v_mfma_f32_16x16x32_bf16 v[90:93], v[142:145], v[212:215], v[90:93]
	v_mfma_f32_16x16x32_bf16 v[78:81], v[134:137], v[220:223], v[78:81]
	v_mfma_f32_16x16x32_bf16 v[74:77], v[142:145], v[220:223], v[74:77]
	v_mfma_f32_16x16x32_bf16 v[118:121], v[166:169], v[182:185], 0
	v_mfma_f32_16x16x32_bf16 v[114:117], v[174:177], v[182:185], 0
	v_mfma_f32_16x16x32_bf16 v[102:105], v[166:169], v[200:203], 0
	v_mfma_f32_16x16x32_bf16 v[98:101], v[174:177], v[200:203], 0
	v_mfma_f32_16x16x32_bf16 v[86:89], v[166:169], v[208:211], 0
	v_mfma_f32_16x16x32_bf16 v[82:85], v[174:177], v[208:211], 0
	v_mfma_f32_16x16x32_bf16 v[70:73], v[166:169], v[216:219], 0
	v_mfma_f32_16x16x32_bf16 v[66:69], v[174:177], v[216:219], 0
	v_mfma_f32_16x16x32_bf16 v[118:121], v[170:173], v[186:189], v[118:121]
	v_mfma_f32_16x16x32_bf16 v[114:117], v[178:181], v[186:189], v[114:117]
	v_mfma_f32_16x16x32_bf16 v[102:105], v[170:173], v[204:207], v[102:105]
	v_mfma_f32_16x16x32_bf16 v[98:101], v[178:181], v[204:207], v[98:101]
	v_mfma_f32_16x16x32_bf16 v[86:89], v[170:173], v[212:215], v[86:89]
	v_mfma_f32_16x16x32_bf16 v[82:85], v[178:181], v[212:215], v[82:85]
	v_mfma_f32_16x16x32_bf16 v[70:73], v[170:173], v[220:223], v[70:73]
	v_mfma_f32_16x16x32_bf16 v[66:69], v[178:181], v[220:223], v[66:69]
	s_barrier
	s_add_i32 s94, s7, s97
	v_lshl_add_u64 v[190:191], s[90:91], 0, v[148:149]
	s_mov_b32 m0, s94
	ds_read_b128 v[182:185], v195 offset:16384
	ds_read_b128 v[186:189], v195 offset:17408
	ds_read_b128 v[200:203], v195 offset:18432
	ds_read_b128 v[204:207], v195 offset:19456
	ds_read_b128 v[208:211], v195 offset:20480
	ds_read_b128 v[212:215], v195 offset:21504
	ds_read_b128 v[216:219], v195 offset:22528
	ds_read_b128 v[220:223], v195 offset:23552
	global_load_lds_dwordx4 v[190:191], off
	s_add_i32 m0, s94, 0x2000
	s_add_u32 s94, s90, 0x40000
	v_lshl_add_u64 v[224:225], s[90:91], 0, v[152:153]
	s_addc_u32 s95, s91, 0
	s_add_i32 s18, s64, s97
	global_load_lds_dwordx4 v[224:225], off
	v_lshl_add_u64 v[226:227], s[94:95], 0, v[148:149]
	s_mov_b32 m0, s18
	v_lshl_add_u64 v[228:229], s[92:93], 0, v[150:151]
	global_load_lds_dwordx4 v[226:227], off
	v_lshl_add_u64 v[226:227], s[94:95], 0, v[152:153]
	s_add_i32 m0, s18, 0x2000
	s_nop 0
	global_load_lds_dwordx4 v[226:227], off
	v_lshl_add_u64 v[226:227], s[92:93], 0, v[146:147]
	s_mov_b32 m0, s58
	s_nop 0
	global_load_lds_dwordx4 v[226:227], off
	s_mov_b32 m0, s59
	s_nop 0
	global_load_lds_dwordx4 v[228:229], off
	s_waitcnt vmcnt(8)
	s_waitcnt lgkmcnt(0)
	s_barrier
	s_waitcnt lgkmcnt(0)
	v_mfma_f32_16x16x32_bf16 v[62:65], v[130:133], v[182:185], 0
	v_mfma_f32_16x16x32_bf16 v[58:61], v[138:141], v[182:185], 0
	v_mfma_f32_16x16x32_bf16 v[46:49], v[130:133], v[200:203], 0
	v_mfma_f32_16x16x32_bf16 v[42:45], v[138:141], v[200:203], 0
	v_mfma_f32_16x16x32_bf16 v[30:33], v[130:133], v[208:211], 0
	v_mfma_f32_16x16x32_bf16 v[26:29], v[138:141], v[208:211], 0
	v_mfma_f32_16x16x32_bf16 v[14:17], v[130:133], v[216:219], 0
	v_mfma_f32_16x16x32_bf16 v[10:13], v[138:141], v[216:219], 0
	v_mfma_f32_16x16x32_bf16 v[62:65], v[134:137], v[186:189], v[62:65]
	v_mfma_f32_16x16x32_bf16 v[58:61], v[142:145], v[186:189], v[58:61]
	v_mfma_f32_16x16x32_bf16 v[46:49], v[134:137], v[204:207], v[46:49]
	v_mfma_f32_16x16x32_bf16 v[42:45], v[142:145], v[204:207], v[42:45]
	v_mfma_f32_16x16x32_bf16 v[30:33], v[134:137], v[212:215], v[30:33]
	v_mfma_f32_16x16x32_bf16 v[26:29], v[142:145], v[212:215], v[26:29]
	v_mfma_f32_16x16x32_bf16 v[14:17], v[134:137], v[220:223], v[14:17]
	v_mfma_f32_16x16x32_bf16 v[10:13], v[142:145], v[220:223], v[10:13]
	v_mfma_f32_16x16x32_bf16 v[54:57], v[166:169], v[182:185], 0
	v_mfma_f32_16x16x32_bf16 v[50:53], v[174:177], v[182:185], 0
	v_mfma_f32_16x16x32_bf16 v[38:41], v[166:169], v[200:203], 0
	v_mfma_f32_16x16x32_bf16 v[34:37], v[174:177], v[200:203], 0
	v_mfma_f32_16x16x32_bf16 v[22:25], v[166:169], v[208:211], 0
	v_mfma_f32_16x16x32_bf16 v[18:21], v[174:177], v[208:211], 0
	v_mfma_f32_16x16x32_bf16 v[6:9], v[166:169], v[216:219], 0
	v_mfma_f32_16x16x32_bf16 v[2:5], v[174:177], v[216:219], 0
	v_mfma_f32_16x16x32_bf16 v[54:57], v[170:173], v[186:189], v[54:57]
	v_mfma_f32_16x16x32_bf16 v[50:53], v[178:181], v[186:189], v[50:53]
	v_mfma_f32_16x16x32_bf16 v[38:41], v[170:173], v[204:207], v[38:41]
	v_mfma_f32_16x16x32_bf16 v[34:37], v[178:181], v[204:207], v[34:37]
	v_mfma_f32_16x16x32_bf16 v[22:25], v[170:173], v[212:215], v[22:25]
	v_mfma_f32_16x16x32_bf16 v[18:21], v[178:181], v[212:215], v[18:21]
	v_mfma_f32_16x16x32_bf16 v[6:9], v[170:173], v[220:223], v[6:9]
	v_mfma_f32_16x16x32_bf16 v[2:5], v[178:181], v[220:223], v[2:5]
	s_barrier
; #define PG8_STAGE(bufoff, gbase, voff) do { _Pragma("unroll") for (int _i = 0; _i < 2; ++_i) \
;         __builtin_amdgcn_global_load_lds((const unsigned*)((const char*)(gbase) + (voff)[_i]), (PG8_LAS unsigned*)(lds + (bufoff) + ldsw + _i * 8192), 16, 0, 0); } while (0)
; #define PG8_LDA(dst, b, h) do { _Pragma("unroll") for (int m = 0; m < 4; ++m) _Pragma("unroll") for (int k = 0; k < 2; ++k) dst[m][k] = *(const PG8_LAS bf16x8*)(lds + PG8_SA(b, h) + aoff + m * 2048 + k * 1024); } while (0)
; #define PG8_WAIT_V(n) asm volatile("s_waitcnt vmcnt(" #n ")" ::: "memory")
; #define PG8_BAR __builtin_amdgcn_s_barrier()
; template <class Epi, class Sched, bool ALIGN_EPI = false, bool SP2 = false>
; __device__ __forceinline__ void gemm_phase(PG8_LAS unsigned char* lds, const Gemm g, const Sched& S, const Epi& E) {
;     ...
;         for (int t = 0; t < nt; t += 2) {
;             if constexpr (Epi::HAS_MID) { if (t == nt / 2) E.mid(acc, cur, wr, wc, fr, fq); }
;             const bool last = (t == nt - 2);
;             const char* a1 = cA + (size_t)(t + 1) * kstep;
;             const char* a2 = last ? nA : cA + (size_t)(t + 2) * kstep; const char* b2 = last ? nB : cB + (size_t)(t + 2) * kstep;
;             const char* a3 = a2 + kstep; const char* b3 = b2 + kstep;
;             if (last && has_next) S.a_ready(nxt);
;             if constexpr (SP2) {
;             PG8_LDB(B0, 0, 0); PG8_LDB(B1, 0, 1); PG8_SCHED; PG8_LDA(At, 0, 0); PG8_STAGE(PG8_SA(1, 1), a1 + hstep, voffA);
;             PG8_WAIT_V(8); PG8_WAIT_L(0); PG8_BAR; PG8_MMA(0, 0, At, B0); PG8_MMA(0, 1, At, B1); PG8_BAR; PG8_SCHED;
;             PG8_LDA(At, 0, 1); PG8_STAGE(PG8_SB(0, 0), b2, voffB); PG8_STAGE(PG8_SB(0, 1), b2 + hstep, voffB); PG8_STAGE(PG8_SA(0, 0), a2, voffA);
;             PG8_WAIT_V(8); PG8_WAIT_L(0); PG8_BAR; PG8_MMA(1, 0, At, B0); PG8_MMA(1, 1, At, B1); PG8_BAR; PG8_SCHED;
;             PG8_LDB(B0, 1, 0); PG8_LDB(B1, 1, 1); PG8_SCHED; PG8_LDA(At, 1, 0); PG8_STAGE(PG8_SA(0, 1), a2 + hstep, voffA);
;             PG8_WAIT_V(8); PG8_WAIT_L(0); PG8_BAR; PG8_MMA(0, 0, At, B0); PG8_MMA(0, 1, At, B1); PG8_BAR; PG8_SCHED;
;             PG8_LDA(At, 1, 1); PG8_STAGE(PG8_SB(1, 0), b3, voffB); PG8_STAGE(PG8_SB(1, 1), b3 + hstep, voffB); PG8_STAGE(PG8_SA(1, 0), a3, voffA);
;             PG8_WAIT_V(8); PG8_WAIT_L(0); PG8_BAR; PG8_MMA(1, 0, At, B0); PG8_MMA(1, 1, At, B1); PG8_BAR; PG8_SCHED;
	s_add_i32 s18, 0, 0x18000
	s_add_i32 s94, 0, 0x1c000
	v_add_u32_e32 v142, s18, v192
	v_add_u32_e32 v154, s94, v192
	ds_read_b128 v[130:133], v142
	ds_read_b128 v[134:137], v142 offset:1024
	ds_read_b128 v[138:141], v142 offset:2048
	ds_read_b128 v[142:145], v142 offset:3072
	ds_read_b128 v[166:169], v154
	ds_read_b128 v[170:173], v154 offset:1024
	ds_read_b128 v[174:177], v154 offset:2048
	ds_read_b128 v[178:181], v154 offset:3072
	s_add_u32 s92, s92, 0x40000
	s_addc_u32 s93, s93, 0
	s_mov_b32 m0, s56
	v_lshl_add_u64 v[230:231], s[92:93], 0, v[146:147]
	ds_read_b128 v[182:185], v195 offset:32768
	ds_read_b128 v[186:189], v195 offset:33792
	ds_read_b128 v[200:203], v195 offset:34816
	ds_read_b128 v[204:207], v195 offset:35840
	ds_read_b128 v[208:211], v195 offset:36864
	ds_read_b128 v[212:215], v195 offset:37888
	ds_read_b128 v[216:219], v195 offset:38912
	ds_read_b128 v[220:223], v195 offset:39936
	global_load_lds_dwordx4 v[230:231], off
	v_lshl_add_u64 v[230:231], s[92:93], 0, v[150:151]
	s_mov_b32 m0, s57
	s_nop 0
	global_load_lds_dwordx4 v[230:231], off
	s_waitcnt vmcnt(8)
	s_waitcnt lgkmcnt(0)
	s_barrier
	s_waitcnt lgkmcnt(0)
	v_mfma_f32_16x16x32_bf16 v[126:129], v[130:133], v[182:185], v[126:129]
	v_mfma_f32_16x16x32_bf16 v[122:125], v[138:141], v[182:185], v[122:125]
	v_mfma_f32_16x16x32_bf16 v[110:113], v[130:133], v[200:203], v[110:113]
	v_mfma_f32_16x16x32_bf16 v[106:109], v[138:141], v[200:203], v[106:109]
	v_mfma_f32_16x16x32_bf16 v[94:97], v[130:133], v[208:211], v[94:97]
	v_mfma_f32_16x16x32_bf16 v[90:93], v[138:141], v[208:211], v[90:93]
	v_mfma_f32_16x16x32_bf16 v[78:81], v[130:133], v[216:219], v[78:81]
	v_mfma_f32_16x16x32_bf16 v[74:77], v[138:141], v[216:219], v[74:77]
	v_mfma_f32_16x16x32_bf16 v[126:129], v[134:137], v[186:189], v[126:129]
	v_mfma_f32_16x16x32_bf16 v[122:125], v[142:145], v[186:189], v[122:125]
	v_mfma_f32_16x16x32_bf16 v[110:113], v[134:137], v[204:207], v[110:113]
	v_mfma_f32_16x16x32_bf16 v[106:109], v[142:145], v[204:207], v[106:109]
	v_mfma_f32_16x16x32_bf16 v[94:97], v[134:137], v[212:215], v[94:97]
	v_mfma_f32_16x16x32_bf16 v[90:93], v[142:145], v[212:215], v[90:93]
	v_mfma_f32_16x16x32_bf16 v[78:81], v[134:137], v[220:223], v[78:81]
	v_mfma_f32_16x16x32_bf16 v[74:77], v[142:145], v[220:223], v[74:77]
	v_mfma_f32_16x16x32_bf16 v[118:121], v[166:169], v[182:185], v[118:121]
	v_mfma_f32_16x16x32_bf16 v[114:117], v[174:177], v[182:185], v[114:117]
	v_mfma_f32_16x16x32_bf16 v[102:105], v[166:169], v[200:203], v[102:105]
	v_mfma_f32_16x16x32_bf16 v[98:101], v[174:177], v[200:203], v[98:101]
	v_mfma_f32_16x16x32_bf16 v[86:89], v[166:169], v[208:211], v[86:89]
	v_mfma_f32_16x16x32_bf16 v[82:85], v[174:177], v[208:211], v[82:85]
	v_mfma_f32_16x16x32_bf16 v[70:73], v[166:169], v[216:219], v[70:73]
	v_mfma_f32_16x16x32_bf16 v[66:69], v[174:177], v[216:219], v[66:69]
	v_mfma_f32_16x16x32_bf16 v[118:121], v[170:173], v[186:189], v[118:121]
	v_mfma_f32_16x16x32_bf16 v[114:117], v[178:181], v[186:189], v[114:117]
	v_mfma_f32_16x16x32_bf16 v[102:105], v[170:173], v[204:207], v[102:105]
	v_mfma_f32_16x16x32_bf16 v[98:101], v[178:181], v[204:207], v[98:101]
	v_mfma_f32_16x16x32_bf16 v[86:89], v[170:173], v[212:215], v[86:89]
	v_mfma_f32_16x16x32_bf16 v[82:85], v[178:181], v[212:215], v[82:85]
	v_mfma_f32_16x16x32_bf16 v[70:73], v[170:173], v[220:223], v[70:73]
	v_mfma_f32_16x16x32_bf16 v[66:69], v[178:181], v[220:223], v[66:69]
	s_barrier
	s_add_i32 s18, s18, s97
	v_lshl_add_u64 v[190:191], v[190:191], 0, s[74:75]
	s_mov_b32 m0, s18
	ds_read_b128 v[182:185], v195 offset:49152
	ds_read_b128 v[186:189], v195 offset:50176
	ds_read_b128 v[200:203], v195 offset:51200
	ds_read_b128 v[204:207], v195 offset:52224
	ds_read_b128 v[208:211], v195 offset:53248
	ds_read_b128 v[212:215], v195 offset:54272
	ds_read_b128 v[216:219], v195 offset:55296
	ds_read_b128 v[220:223], v195 offset:56320
	global_load_lds_dwordx4 v[190:191], off
	s_add_i32 m0, s18, 0x2000
	s_add_u32 s90, s90, 0x40080
	v_lshl_add_u64 v[190:191], v[224:225], 0, s[74:75]
	s_addc_u32 s91, s91, 0
	s_add_i32 s18, s94, s97
	global_load_lds_dwordx4 v[190:191], off
	v_lshl_add_u64 v[190:191], s[90:91], 0, v[148:149]
	s_mov_b32 m0, s18
	s_nop 0
	global_load_lds_dwordx4 v[190:191], off
	v_lshl_add_u64 v[190:191], s[90:91], 0, v[152:153]
	s_add_i32 m0, s18, 0x2000
	s_nop 0
	global_load_lds_dwordx4 v[190:191], off
	v_lshl_add_u64 v[190:191], v[226:227], 0, s[74:75]
	s_mov_b32 m0, s19
	s_nop 0
	global_load_lds_dwordx4 v[190:191], off
	v_lshl_add_u64 v[190:191], v[228:229], 0, s[74:75]
	s_mov_b32 m0, s66
	s_nop 0
	global_load_lds_dwordx4 v[190:191], off
	s_waitcnt vmcnt(8)
	s_waitcnt lgkmcnt(0)
	s_barrier
	s_waitcnt lgkmcnt(0)
	v_mfma_f32_16x16x32_bf16 v[62:65], v[130:133], v[182:185], v[62:65]
	v_mfma_f32_16x16x32_bf16 v[58:61], v[138:141], v[182:185], v[58:61]
	v_mfma_f32_16x16x32_bf16 v[46:49], v[130:133], v[200:203], v[46:49]
	v_mfma_f32_16x16x32_bf16 v[42:45], v[138:141], v[200:203], v[42:45]
	v_mfma_f32_16x16x32_bf16 v[30:33], v[130:133], v[208:211], v[30:33]
	v_mfma_f32_16x16x32_bf16 v[26:29], v[138:141], v[208:211], v[26:29]
	v_mfma_f32_16x16x32_bf16 v[14:17], v[130:133], v[216:219], v[14:17]
	v_mfma_f32_16x16x32_bf16 v[10:13], v[138:141], v[216:219], v[10:13]
	v_mfma_f32_16x16x32_bf16 v[62:65], v[134:137], v[186:189], v[62:65]
	v_mfma_f32_16x16x32_bf16 v[58:61], v[142:145], v[186:189], v[58:61]
	v_mfma_f32_16x16x32_bf16 v[46:49], v[134:137], v[204:207], v[46:49]
	v_mfma_f32_16x16x32_bf16 v[42:45], v[142:145], v[204:207], v[42:45]
	v_mfma_f32_16x16x32_bf16 v[30:33], v[134:137], v[212:215], v[30:33]
	v_mfma_f32_16x16x32_bf16 v[26:29], v[142:145], v[212:215], v[26:29]
	v_mfma_f32_16x16x32_bf16 v[14:17], v[134:137], v[220:223], v[14:17]
	v_mfma_f32_16x16x32_bf16 v[10:13], v[142:145], v[220:223], v[10:13]
	v_mfma_f32_16x16x32_bf16 v[54:57], v[166:169], v[182:185], v[54:57]
	v_mfma_f32_16x16x32_bf16 v[50:53], v[174:177], v[182:185], v[50:53]
	v_mfma_f32_16x16x32_bf16 v[38:41], v[166:169], v[200:203], v[38:41]
	v_mfma_f32_16x16x32_bf16 v[34:37], v[174:177], v[200:203], v[34:37]
	v_mfma_f32_16x16x32_bf16 v[22:25], v[166:169], v[208:211], v[22:25]
	v_mfma_f32_16x16x32_bf16 v[18:21], v[174:177], v[208:211], v[18:21]
	v_mfma_f32_16x16x32_bf16 v[6:9], v[166:169], v[216:219], v[6:9]
	v_mfma_f32_16x16x32_bf16 v[2:5], v[174:177], v[216:219], v[2:5]
	v_mfma_f32_16x16x32_bf16 v[54:57], v[170:173], v[186:189], v[54:57]
	v_mfma_f32_16x16x32_bf16 v[50:53], v[178:181], v[186:189], v[50:53]
	v_mfma_f32_16x16x32_bf16 v[38:41], v[170:173], v[204:207], v[38:41]
	v_mfma_f32_16x16x32_bf16 v[34:37], v[178:181], v[204:207], v[34:37]
	v_mfma_f32_16x16x32_bf16 v[22:25], v[170:173], v[212:215], v[22:25]
	v_mfma_f32_16x16x32_bf16 v[18:21], v[178:181], v[212:215], v[18:21]
	v_mfma_f32_16x16x32_bf16 v[6:9], v[170:173], v[220:223], v[6:9]
	v_mfma_f32_16x16x32_bf16 v[2:5], v[178:181], v[220:223], v[2:5]
	s_barrier
	s_add_i32 vcc_hi, vcc_hi, 2
	s_add_u32 s88, s88, 0x100
	s_addc_u32 s89, s89, 0
	s_add_u32 s83, s83, 0x100
	s_addc_u32 vcc_lo, vcc_lo, 0
	s_cmp_gt_u32 vcc_hi, 13

; #define PG8_WAIT_V(n) asm volatile("s_waitcnt vmcnt(" #n ")" ::: "memory")
; #define PG8_BAR __builtin_amdgcn_s_barrier()
; template <class Epi, class Sched, bool ALIGN_EPI = false, bool SP2 = false>
; __device__ __forceinline__ void gemm_phase(PG8_LAS unsigned char* lds, const Gemm g, const Sched& S, const Epi& E) {
;     ...
;     PG8_WAIT_V(0);
;     if constexpr (!ALIGN_EPI) { if (wr == 0) PG8_BAR; }
;     PG8_BAR;
.LBB0_242:
	s_setprio 0
	s_waitcnt vmcnt(0)
	v_readlane_b32 s18, v236, 4
	v_readlane_b32 s98, v236, 9
	v_readlane_b32 s72, v236, 8
	v_readlane_b32 s84, v236, 7
	v_readlane_b32 s85, v236, 6
	v_readlane_b32 s19, v236, 5
	s_barrier
	s_cmp_lt_i32 s53, 3
	s_cbranch_scc1 .LBB0_315
